# stack + post phase scan-carry fold: 32 chunk-summary loads per round in flight together
# speedup vs baseline: 1.0103x; 1.0026x over previous
.LBB0_639:
	s_add_i32 s9, s8, 0
	s_cmp_lt_u32 s9, s10
	s_cselect_b32 s86, s9, 0
	s_lshl_b64 s[6:7], s[86:87], 11
	v_lshl_add_u64 v[166:167], v[80:81], 0, s[6:7]
	v_lshl_add_u64 v[168:169], v[82:83], 0, s[6:7]
	global_load_dword v134, v[166:167], off
	global_load_dword v150, v[168:169], off
	s_add_i32 s9, s8, 1
	s_cmp_lt_u32 s9, s10
	s_cselect_b32 s86, s9, 0
	s_lshl_b64 s[6:7], s[86:87], 11
	v_lshl_add_u64 v[166:167], v[80:81], 0, s[6:7]
	v_lshl_add_u64 v[168:169], v[82:83], 0, s[6:7]
	global_load_dword v135, v[166:167], off
	global_load_dword v151, v[168:169], off
	s_add_i32 s9, s8, 2
	s_cmp_lt_u32 s9, s10
	s_cselect_b32 s86, s9, 0
	s_lshl_b64 s[6:7], s[86:87], 11
	v_lshl_add_u64 v[166:167], v[80:81], 0, s[6:7]
	v_lshl_add_u64 v[168:169], v[82:83], 0, s[6:7]
	global_load_dword v136, v[166:167], off
	global_load_dword v152, v[168:169], off
	s_add_i32 s9, s8, 3
	s_cmp_lt_u32 s9, s10
	s_cselect_b32 s86, s9, 0
	s_lshl_b64 s[6:7], s[86:87], 11
	v_lshl_add_u64 v[166:167], v[80:81], 0, s[6:7]
	v_lshl_add_u64 v[168:169], v[82:83], 0, s[6:7]
	global_load_dword v137, v[166:167], off
	global_load_dword v153, v[168:169], off
	s_add_i32 s9, s8, 4
	s_cmp_lt_u32 s9, s10
	s_cselect_b32 s86, s9, 0
	s_lshl_b64 s[6:7], s[86:87], 11
	v_lshl_add_u64 v[166:167], v[80:81], 0, s[6:7]
	v_lshl_add_u64 v[168:169], v[82:83], 0, s[6:7]
	global_load_dword v138, v[166:167], off
	global_load_dword v154, v[168:169], off
	s_add_i32 s9, s8, 5
	s_cmp_lt_u32 s9, s10
	s_cselect_b32 s86, s9, 0
	s_lshl_b64 s[6:7], s[86:87], 11
	v_lshl_add_u64 v[166:167], v[80:81], 0, s[6:7]
	v_lshl_add_u64 v[168:169], v[82:83], 0, s[6:7]
	global_load_dword v139, v[166:167], off
	global_load_dword v155, v[168:169], off
	s_add_i32 s9, s8, 6
	s_cmp_lt_u32 s9, s10
	s_cselect_b32 s86, s9, 0
	s_lshl_b64 s[6:7], s[86:87], 11
	v_lshl_add_u64 v[166:167], v[80:81], 0, s[6:7]
	v_lshl_add_u64 v[168:169], v[82:83], 0, s[6:7]
	global_load_dword v140, v[166:167], off
	global_load_dword v156, v[168:169], off
	s_add_i32 s9, s8, 7
	s_cmp_lt_u32 s9, s10
	s_cselect_b32 s86, s9, 0
	s_lshl_b64 s[6:7], s[86:87], 11
	v_lshl_add_u64 v[166:167], v[80:81], 0, s[6:7]
	v_lshl_add_u64 v[168:169], v[82:83], 0, s[6:7]
	global_load_dword v141, v[166:167], off
	global_load_dword v157, v[168:169], off
	s_add_i32 s9, s8, 8
	s_cmp_lt_u32 s9, s10
	s_cselect_b32 s86, s9, 0
	s_lshl_b64 s[6:7], s[86:87], 11
	v_lshl_add_u64 v[166:167], v[80:81], 0, s[6:7]
	v_lshl_add_u64 v[168:169], v[82:83], 0, s[6:7]
	global_load_dword v142, v[166:167], off
	global_load_dword v158, v[168:169], off
	s_add_i32 s9, s8, 9
	s_cmp_lt_u32 s9, s10
	s_cselect_b32 s86, s9, 0
	s_lshl_b64 s[6:7], s[86:87], 11
	v_lshl_add_u64 v[166:167], v[80:81], 0, s[6:7]
	v_lshl_add_u64 v[168:169], v[82:83], 0, s[6:7]
	global_load_dword v143, v[166:167], off
	global_load_dword v159, v[168:169], off
	s_add_i32 s9, s8, 10
	s_cmp_lt_u32 s9, s10
	s_cselect_b32 s86, s9, 0
	s_lshl_b64 s[6:7], s[86:87], 11
	v_lshl_add_u64 v[166:167], v[80:81], 0, s[6:7]
	v_lshl_add_u64 v[168:169], v[82:83], 0, s[6:7]
	global_load_dword v144, v[166:167], off
	global_load_dword v160, v[168:169], off
	s_add_i32 s9, s8, 11
	s_cmp_lt_u32 s9, s10
	s_cselect_b32 s86, s9, 0
	s_lshl_b64 s[6:7], s[86:87], 11
	v_lshl_add_u64 v[166:167], v[80:81], 0, s[6:7]
	v_lshl_add_u64 v[168:169], v[82:83], 0, s[6:7]
	global_load_dword v145, v[166:167], off
	global_load_dword v161, v[168:169], off
	s_add_i32 s9, s8, 12
	s_cmp_lt_u32 s9, s10
	s_cselect_b32 s86, s9, 0
	s_lshl_b64 s[6:7], s[86:87], 11
	v_lshl_add_u64 v[166:167], v[80:81], 0, s[6:7]
	v_lshl_add_u64 v[168:169], v[82:83], 0, s[6:7]
	global_load_dword v146, v[166:167], off
	global_load_dword v162, v[168:169], off
	s_add_i32 s9, s8, 13
	s_cmp_lt_u32 s9, s10
	s_cselect_b32 s86, s9, 0
	s_lshl_b64 s[6:7], s[86:87], 11
	v_lshl_add_u64 v[166:167], v[80:81], 0, s[6:7]
	v_lshl_add_u64 v[168:169], v[82:83], 0, s[6:7]
	global_load_dword v147, v[166:167], off
	global_load_dword v163, v[168:169], off
	s_add_i32 s9, s8, 14
	s_cmp_lt_u32 s9, s10
	s_cselect_b32 s86, s9, 0
	s_lshl_b64 s[6:7], s[86:87], 11
	v_lshl_add_u64 v[166:167], v[80:81], 0, s[6:7]
	v_lshl_add_u64 v[168:169], v[82:83], 0, s[6:7]
	global_load_dword v148, v[166:167], off
	global_load_dword v164, v[168:169], off
	s_add_i32 s9, s8, 15
	s_cmp_lt_u32 s9, s10
	s_cselect_b32 s86, s9, 0
	s_lshl_b64 s[6:7], s[86:87], 11
	v_lshl_add_u64 v[166:167], v[80:81], 0, s[6:7]
	v_lshl_add_u64 v[168:169], v[82:83], 0, s[6:7]
	global_load_dword v149, v[166:167], off
	global_load_dword v165, v[168:169], off
	s_waitcnt vmcnt(0)
	s_add_i32 s9, s8, 0
	s_cmp_lt_u32 s9, s10
	s_cselect_b64 s[6:7], -1, 0
	v_cndmask_b32_e64 v166, 0, 1.0, s[6:7]
	v_sub_f32_e32 v167, 1.0, v166
	v_fmac_f32_e32 v167, v134, v166
	v_mul_f32_e32 v168, v166, v150
	v_fma_f32 v126, v167, v126, v168
	s_add_i32 s9, s8, 1
	s_cmp_lt_u32 s9, s10
	s_cselect_b64 s[6:7], -1, 0
	v_cndmask_b32_e64 v166, 0, 1.0, s[6:7]
	v_sub_f32_e32 v167, 1.0, v166
	v_fmac_f32_e32 v167, v135, v166
	v_mul_f32_e32 v168, v166, v151
	v_fma_f32 v126, v167, v126, v168
	s_add_i32 s9, s8, 2
	s_cmp_lt_u32 s9, s10
	s_cselect_b64 s[6:7], -1, 0
	v_cndmask_b32_e64 v166, 0, 1.0, s[6:7]
	v_sub_f32_e32 v167, 1.0, v166
	v_fmac_f32_e32 v167, v136, v166
	v_mul_f32_e32 v168, v166, v152
	v_fma_f32 v126, v167, v126, v168
	s_add_i32 s9, s8, 3
	s_cmp_lt_u32 s9, s10
	s_cselect_b64 s[6:7], -1, 0
	v_cndmask_b32_e64 v166, 0, 1.0, s[6:7]
	v_sub_f32_e32 v167, 1.0, v166
	v_fmac_f32_e32 v167, v137, v166
	v_mul_f32_e32 v168, v166, v153
	v_fma_f32 v126, v167, v126, v168
	s_add_i32 s9, s8, 4
	s_cmp_lt_u32 s9, s10
	s_cselect_b64 s[6:7], -1, 0
	v_cndmask_b32_e64 v166, 0, 1.0, s[6:7]
	v_sub_f32_e32 v167, 1.0, v166
	v_fmac_f32_e32 v167, v138, v166
	v_mul_f32_e32 v168, v166, v154
	v_fma_f32 v126, v167, v126, v168
	s_add_i32 s9, s8, 5
	s_cmp_lt_u32 s9, s10
	s_cselect_b64 s[6:7], -1, 0
	v_cndmask_b32_e64 v166, 0, 1.0, s[6:7]
	v_sub_f32_e32 v167, 1.0, v166
	v_fmac_f32_e32 v167, v139, v166
	v_mul_f32_e32 v168, v166, v155
	v_fma_f32 v126, v167, v126, v168
	s_add_i32 s9, s8, 6
	s_cmp_lt_u32 s9, s10
	s_cselect_b64 s[6:7], -1, 0
	v_cndmask_b32_e64 v166, 0, 1.0, s[6:7]
	v_sub_f32_e32 v167, 1.0, v166
	v_fmac_f32_e32 v167, v140, v166
	v_mul_f32_e32 v168, v166, v156
	v_fma_f32 v126, v167, v126, v168
	s_add_i32 s9, s8, 7
	s_cmp_lt_u32 s9, s10
	s_cselect_b64 s[6:7], -1, 0
	v_cndmask_b32_e64 v166, 0, 1.0, s[6:7]
	v_sub_f32_e32 v167, 1.0, v166
	v_fmac_f32_e32 v167, v141, v166
	v_mul_f32_e32 v168, v166, v157
	v_fma_f32 v126, v167, v126, v168
	s_add_i32 s9, s8, 8
	s_cmp_lt_u32 s9, s10
	s_cselect_b64 s[6:7], -1, 0
	v_cndmask_b32_e64 v166, 0, 1.0, s[6:7]
	v_sub_f32_e32 v167, 1.0, v166
	v_fmac_f32_e32 v167, v142, v166
	v_mul_f32_e32 v168, v166, v158
	v_fma_f32 v126, v167, v126, v168
	s_add_i32 s9, s8, 9
	s_cmp_lt_u32 s9, s10
	s_cselect_b64 s[6:7], -1, 0
	v_cndmask_b32_e64 v166, 0, 1.0, s[6:7]
	v_sub_f32_e32 v167, 1.0, v166
	v_fmac_f32_e32 v167, v143, v166
	v_mul_f32_e32 v168, v166, v159
	v_fma_f32 v126, v167, v126, v168
	s_add_i32 s9, s8, 10
	s_cmp_lt_u32 s9, s10
	s_cselect_b64 s[6:7], -1, 0
	v_cndmask_b32_e64 v166, 0, 1.0, s[6:7]
	v_sub_f32_e32 v167, 1.0, v166
	v_fmac_f32_e32 v167, v144, v166
	v_mul_f32_e32 v168, v166, v160
	v_fma_f32 v126, v167, v126, v168
	s_add_i32 s9, s8, 11
	s_cmp_lt_u32 s9, s10
	s_cselect_b64 s[6:7], -1, 0
	v_cndmask_b32_e64 v166, 0, 1.0, s[6:7]
	v_sub_f32_e32 v167, 1.0, v166
	v_fmac_f32_e32 v167, v145, v166
	v_mul_f32_e32 v168, v166, v161
	v_fma_f32 v126, v167, v126, v168
	s_add_i32 s9, s8, 12
	s_cmp_lt_u32 s9, s10
	s_cselect_b64 s[6:7], -1, 0
	v_cndmask_b32_e64 v166, 0, 1.0, s[6:7]
	v_sub_f32_e32 v167, 1.0, v166
	v_fmac_f32_e32 v167, v146, v166
	v_mul_f32_e32 v168, v166, v162
	v_fma_f32 v126, v167, v126, v168
	s_add_i32 s9, s8, 13
	s_cmp_lt_u32 s9, s10
	s_cselect_b64 s[6:7], -1, 0
	v_cndmask_b32_e64 v166, 0, 1.0, s[6:7]
	v_sub_f32_e32 v167, 1.0, v166
	v_fmac_f32_e32 v167, v147, v166
	v_mul_f32_e32 v168, v166, v163
	v_fma_f32 v126, v167, v126, v168
	s_add_i32 s9, s8, 14
	s_cmp_lt_u32 s9, s10
	s_cselect_b64 s[6:7], -1, 0
	v_cndmask_b32_e64 v166, 0, 1.0, s[6:7]
	v_sub_f32_e32 v167, 1.0, v166
	v_fmac_f32_e32 v167, v148, v166
	v_mul_f32_e32 v168, v166, v164
	v_fma_f32 v126, v167, v126, v168
	s_add_i32 s9, s8, 15
	s_cmp_lt_u32 s9, s10
	s_cselect_b64 s[6:7], -1, 0
	v_cndmask_b32_e64 v166, 0, 1.0, s[6:7]
	v_sub_f32_e32 v167, 1.0, v166
	v_fmac_f32_e32 v167, v149, v166
	v_mul_f32_e32 v168, v166, v165
	v_fma_f32 v126, v167, v126, v168
	s_add_i32 s8, s8, 16
	s_cmp_lt_u32 s8, s10
	s_cbranch_scc1 .LBB0_639
	v_readlane_b32 s86, v254, 13
	s_branch .LBB0_642
